# adds: GLA scan LDS reads batched per MFMA phase; next-chunk staging loads issued inside the VALU phase right after each token's values are consumed
# speedup vs baseline: 1.0133x; 1.0045x over previous
.LBB0_1314:
	s_waitcnt vmcnt(0)
	s_add_i32 s53, s53, s26
	s_cmpk_gt_i32 s53, 0xff
	s_barrier
	s_cbranch_scc1 .LBB0_1333

.LBB0_1316:
	s_add_i32 s74, s74, 64
	s_sub_i32 s75, s75, 64
	s_add_i32 s57, s57, 1
	s_mov_b32 s76, s10
	s_cmpk_eq_i32 s75, 0xffbf
	s_cbranch_scc1 .LBB0_1314
.LBB0_1317:
	s_waitcnt vmcnt(48)
	v_perm_b32 v26, v115, v115, v32
	v_add_f32_e32 v176, 0, v26
	s_waitcnt vmcnt(45)
	v_perm_b32 v26, v119, v119, v32
	v_add_f32_e32 v177, v176, v26
	s_waitcnt vmcnt(42)
	v_perm_b32 v26, v124, v124, v32
	v_add_f32_e32 v178, v177, v26
	s_waitcnt vmcnt(39)
	v_perm_b32 v26, v132, v132, v32
	v_add_f32_e32 v179, v178, v26
	s_waitcnt vmcnt(36)
	v_perm_b32 v26, v136, v136, v32
	v_add_f32_e32 v180, v179, v26
	s_waitcnt vmcnt(33)
	v_perm_b32 v26, v143, v143, v32
	v_add_f32_e32 v181, v180, v26
	s_waitcnt vmcnt(30)
	v_perm_b32 v26, v146, v146, v32
	v_add_f32_e32 v182, v181, v26
	s_waitcnt vmcnt(27)
	v_perm_b32 v26, v149, v149, v32
	v_add_f32_e32 v183, v182, v26
	s_waitcnt vmcnt(24)
	v_perm_b32 v26, v152, v152, v32
	v_add_f32_e32 v184, v183, v26
	s_waitcnt vmcnt(21)
	v_perm_b32 v26, v155, v155, v32
	v_add_f32_e32 v185, v184, v26
	s_waitcnt vmcnt(18)
	v_perm_b32 v26, v158, v158, v32
	v_add_f32_e32 v186, v185, v26
	s_waitcnt vmcnt(15)
	v_perm_b32 v26, v161, v161, v32
	v_add_f32_e32 v187, v186, v26
	s_waitcnt vmcnt(12)
	v_perm_b32 v26, v164, v164, v32
	v_add_f32_e32 v188, v187, v26
	s_waitcnt vmcnt(9)
	v_perm_b32 v26, v167, v167, v32
	v_add_f32_e32 v189, v188, v26
	s_waitcnt vmcnt(6)
	v_perm_b32 v26, v170, v170, v32
	v_add_f32_e32 v190, v189, v26
	s_waitcnt vmcnt(3)
	v_perm_b32 v26, v173, v173, v32
	v_add_f32_e32 v191, v190, v26
	ds_bpermute_b32 v26, v53, v191
	ds_bpermute_b32 v28, v54, v191
	ds_bpermute_b32 v27, v55, v191
	ds_bpermute_b32 v29, v56, v191
	v_cvt_pk_bf16_f32 v22, v2, v3
	v_cvt_pk_bf16_f32 v23, v4, v5
	v_cvt_pk_bf16_f32 v24, v14, v15
	v_cvt_pk_bf16_f32 v25, v16, v17
	s_waitcnt lgkmcnt(0)
	s_barrier
	s_add_i32 s78, s74, 0x100
	s_add_i32 s91, s75, 0xffffe000
	v_readfirstlane_b32 s80, v42
	v_readfirstlane_b32 s81, v43
	s_and_b64 s[98:99], s[70:71], exec
	s_cselect_b32 s32, s74, s75
	s_cselect_b32 s78, s78, s91
	s_cselect_b32 s91, 0, 0xffffffd0
	s_cselect_b32 s83, 0, 0xffffffc1
	s_cselect_b32 s99, 0, -1
	s_mov_b32 s98, 0x2000
	s_cselect_b32 s98, s98, 0xffffe000
	s_add_i32 s32, s32, s65
	s_add_i32 s78, s78, s56
	s_cmp_gt_u32 s57, 2
	s_cselect_b32 s32, s32, s78
	s_cmp_eq_u32 s75, -1
	s_cselect_b32 s32, s76, s32
	v_subrev_u32_e32 v204, s91, v139
	v_subrev_u32_e32 v203, s83, v141
	v_lshlrev_b32_e32 v204, 13, v204
	v_lshlrev_b32_e32 v203, 13, v203
	v_subrev_u32_e32 v200, s80, v46
	v_subrev_u32_e32 v201, s80, v44
	v_subrev_u32_e32 v202, s80, v42
	v_add_u32_e32 v203, v203, v48
	v_add_u32_e32 v200, v200, v204
	v_add_u32_e32 v201, v201, v204
	v_add_u32_e32 v202, v202, v204
	v_subrev_u32_e32 v203, s80, v203
	s_add_i32 s78, s32, s91
	s_lshl_b32 s78, s78, 13
	s_add_u32 s80, s80, s78
	s_addc_u32 s81, s81, 0
	ds_write2_b64 v103, v[22:23], v[24:25] offset1:4
	v_cvt_pk_bf16_f32 v22, v6, v7
	v_cvt_pk_bf16_f32 v23, v8, v9
	v_cvt_pk_bf16_f32 v24, v10, v11
	v_cvt_pk_bf16_f32 v25, v12, v13
	ds_write2_b64 v103, v[22:23], v[24:25] offset0:8 offset1:12
	v_cndmask_b32_e64 v22, v26, 0, s[0:1]
	v_cndmask_b32_e64 v23, 0, v28, s[2:3]
	v_add_f32_e32 v22, v22, v23
	v_cndmask_b32_e64 v23, 0, v27, s[4:5]
	v_add_f32_e32 v192, v22, v23
	v_pk_add_f32 v[22:23], v[26:27], v[28:29]
	v_add_f32_e32 v22, v22, v23
	v_add_f32_e32 v23, v176, v192
	v_exp_f32_e32 v25, v23
	v_perm_b32 v24, v116, v116, v32
	v_exp_f32_e64 v26, -v23
	v_exp_f32_e32 v22, v22
	v_mul_f32_e32 v23, v25, v24
	v_cvt_pk_bf16_f32 v23, v23, s0
	ds_write_b16 v64, v23
	v_add_f32_e32 v23, v177, v192
	v_exp_f32_e32 v24, v23
	v_exp_f32_e64 v27, -v23
	v_perm_b32 v25, v121, v121, v32
	v_perm_b32 v29, v122, v122, v1
	v_perm_b32 v28, v118, v118, v32
	global_load_dword v115, v200, s[80:81]
	global_load_dword v116, v201, s[80:81]
	global_load_dword v118, v202, s[80:81]
	s_add_u32 s80, s80, s98
	s_addc_u32 s81, s81, s99
	global_load_dword v119, v200, s[80:81]
	global_load_dword v121, v201, s[80:81]
	global_load_dword v122, v202, s[80:81]
	s_add_u32 s80, s80, s98
	s_addc_u32 s81, s81, s99
	v_mul_f32_e32 v23, v24, v25
	v_mul_f32_e32 v24, v26, v28
	v_cvt_pk_bf16_f32 v23, v23, s0
	v_cvt_pk_bf16_f32 v24, v24, s0
	ds_write_b16 v64, v24 offset:17408
	v_pk_mul_f32 v[24:25], v[22:23], v[26:27] op_sel_hi:[0,1]
	ds_write_b16 v65, v23
	v_mul_f32_e32 v23, v27, v29
	v_cvt_pk_bf16_f32 v23, v23, s0
	ds_write_b16 v65, v23 offset:17408
	v_add_f32_e32 v23, v178, v192
	v_pk_mul_f32 v[24:25], v[24:25], v[28:29]
	v_exp_f32_e32 v28, v23
	v_perm_b32 v27, v127, v127, v32
	v_exp_f32_e64 v26, -v23
	v_mul_f32_e32 v23, v28, v27
	v_cvt_pk_bf16_f32 v23, v23, s0
	ds_write_b16 v66, v23
	v_add_f32_e32 v23, v179, v192
	v_exp_f32_e32 v28, v23
	v_perm_b32 v177, v133, v133, v32
	v_exp_f32_e64 v27, -v23
	v_mul_f32_e32 v23, v28, v177
	v_perm_b32 v28, v130, v130, v32
	global_load_dword v124, v200, s[80:81]
	global_load_dword v127, v201, s[80:81]
	global_load_dword v130, v202, s[80:81]
	s_add_u32 s80, s80, s98
	s_addc_u32 s81, s81, s99
	v_mul_f32_e32 v176, v26, v28
	v_cvt_pk_bf16_f32 v23, v23, s0
	v_perm_b32 v29, v135, v135, v1
	global_load_dword v132, v200, s[80:81]
	global_load_dword v133, v201, s[80:81]
	global_load_dword v135, v202, s[80:81]
	s_add_u32 s80, s80, s98
	s_addc_u32 s81, s81, s99
	v_cvt_pk_bf16_f32 v176, v176, s0
	ds_write_b16 v66, v176 offset:17408
	v_pk_mul_f32 v[176:177], v[22:23], v[26:27] op_sel_hi:[0,1]
	ds_write_b16 v67, v23
	v_mul_f32_e32 v23, v27, v29
	v_cvt_pk_bf16_f32 v23, v23, s0
	ds_write_b16 v67, v23 offset:17408
	v_add_f32_e32 v23, v180, v192
	v_pk_mul_f32 v[176:177], v[176:177], v[28:29]
	v_exp_f32_e32 v28, v23
	v_perm_b32 v27, v137, v137, v32
	v_exp_f32_e64 v26, -v23
	v_mul_f32_e32 v23, v28, v27
	v_cvt_pk_bf16_f32 v23, v23, s0
	ds_write_b16 v68, v23
	v_add_f32_e32 v23, v181, v192
	v_exp_f32_e32 v28, v23
	v_perm_b32 v179, v144, v144, v32
	v_exp_f32_e64 v27, -v23
	v_mul_f32_e32 v23, v28, v179
	v_perm_b32 v28, v138, v138, v32
	global_load_dword v136, v200, s[80:81]
	global_load_dword v137, v201, s[80:81]
	global_load_dword v138, v202, s[80:81]
	s_add_u32 s80, s80, s98
	s_addc_u32 s81, s81, s99
	v_mul_f32_e32 v178, v26, v28
	v_cvt_pk_bf16_f32 v23, v23, s0
	v_perm_b32 v29, v145, v145, v1
	global_load_dword v143, v200, s[80:81]
	global_load_dword v144, v201, s[80:81]
	global_load_dword v145, v202, s[80:81]
	s_add_u32 s80, s80, s98
	s_addc_u32 s81, s81, s99
	v_cvt_pk_bf16_f32 v178, v178, s0
	ds_write_b16 v68, v178 offset:17408
	v_pk_mul_f32 v[178:179], v[22:23], v[26:27] op_sel_hi:[0,1]
	ds_write_b16 v69, v23
	v_mul_f32_e32 v23, v27, v29
	v_cvt_pk_bf16_f32 v23, v23, s0
	ds_write_b16 v69, v23 offset:17408
	v_add_f32_e32 v23, v182, v192
	v_pk_mul_f32 v[178:179], v[178:179], v[28:29]
	v_exp_f32_e32 v28, v23
	v_perm_b32 v27, v147, v147, v32
	v_exp_f32_e64 v26, -v23
	v_mul_f32_e32 v23, v28, v27
	v_cvt_pk_bf16_f32 v23, v23, s0
	ds_write_b16 v70, v23
	v_add_f32_e32 v23, v183, v192
	v_exp_f32_e32 v28, v23
	v_perm_b32 v181, v150, v150, v32
	v_exp_f32_e64 v27, -v23
	v_mul_f32_e32 v23, v28, v181
	v_perm_b32 v28, v148, v148, v32
	global_load_dword v146, v200, s[80:81]
	global_load_dword v147, v201, s[80:81]
	global_load_dword v148, v202, s[80:81]
	s_add_u32 s80, s80, s98
	s_addc_u32 s81, s81, s99
	v_mul_f32_e32 v180, v26, v28
	v_cvt_pk_bf16_f32 v23, v23, s0
	v_perm_b32 v29, v151, v151, v1
	global_load_dword v149, v200, s[80:81]
	global_load_dword v150, v201, s[80:81]
	global_load_dword v151, v202, s[80:81]
	s_add_u32 s80, s80, s98
	s_addc_u32 s81, s81, s99
	v_cvt_pk_bf16_f32 v180, v180, s0
	ds_write_b16 v70, v180 offset:17408
	v_pk_mul_f32 v[180:181], v[22:23], v[26:27] op_sel_hi:[0,1]
	ds_write_b16 v71, v23
	v_mul_f32_e32 v23, v27, v29
	v_cvt_pk_bf16_f32 v23, v23, s0
	ds_write_b16 v71, v23 offset:17408
	v_add_f32_e32 v23, v184, v192
	v_pk_mul_f32 v[180:181], v[180:181], v[28:29]
	v_exp_f32_e32 v28, v23
	v_perm_b32 v27, v153, v153, v32
	v_exp_f32_e64 v26, -v23
	v_mul_f32_e32 v23, v28, v27
	v_cvt_pk_bf16_f32 v23, v23, s0
	ds_write_b16 v72, v23
	v_add_f32_e32 v23, v185, v192
	v_exp_f32_e32 v28, v23
	v_perm_b32 v183, v156, v156, v32
	v_exp_f32_e64 v27, -v23
	v_mul_f32_e32 v23, v28, v183
	v_perm_b32 v28, v154, v154, v32
	global_load_dword v152, v200, s[80:81]
	global_load_dword v153, v201, s[80:81]
	global_load_dword v154, v202, s[80:81]
	s_add_u32 s80, s80, s98
	s_addc_u32 s81, s81, s99
	v_mul_f32_e32 v182, v26, v28
	v_cvt_pk_bf16_f32 v23, v23, s0
	v_perm_b32 v29, v157, v157, v1
	global_load_dword v155, v200, s[80:81]
	global_load_dword v156, v201, s[80:81]
	global_load_dword v157, v202, s[80:81]
	s_add_u32 s80, s80, s98
	s_addc_u32 s81, s81, s99
	v_cvt_pk_bf16_f32 v182, v182, s0
	ds_write_b16 v72, v182 offset:17408
	v_pk_mul_f32 v[182:183], v[22:23], v[26:27] op_sel_hi:[0,1]
	ds_write_b16 v73, v23
	v_mul_f32_e32 v23, v27, v29
	v_cvt_pk_bf16_f32 v23, v23, s0
	ds_write_b16 v73, v23 offset:17408
	v_add_f32_e32 v23, v186, v192
	v_pk_mul_f32 v[182:183], v[182:183], v[28:29]
	v_exp_f32_e32 v28, v23
	v_perm_b32 v27, v159, v159, v32
	v_exp_f32_e64 v26, -v23
	v_mul_f32_e32 v23, v28, v27
	v_cvt_pk_bf16_f32 v23, v23, s0
	ds_write_b16 v74, v23
	v_add_f32_e32 v23, v187, v192
	v_exp_f32_e32 v28, v23
	v_perm_b32 v185, v162, v162, v32
	v_exp_f32_e64 v27, -v23
	v_mul_f32_e32 v23, v28, v185
	v_perm_b32 v28, v160, v160, v32
	global_load_dword v158, v200, s[80:81]
	global_load_dword v159, v201, s[80:81]
	global_load_dword v160, v202, s[80:81]
	s_add_u32 s80, s80, s98
	s_addc_u32 s81, s81, s99
	v_mul_f32_e32 v184, v26, v28
	v_cvt_pk_bf16_f32 v23, v23, s0
	v_perm_b32 v29, v163, v163, v1
	global_load_dword v161, v200, s[80:81]
	global_load_dword v162, v201, s[80:81]
	global_load_dword v163, v202, s[80:81]
	s_add_u32 s80, s80, s98
	s_addc_u32 s81, s81, s99
	v_cvt_pk_bf16_f32 v184, v184, s0
	ds_write_b16 v74, v184 offset:17408
	v_pk_mul_f32 v[184:185], v[22:23], v[26:27] op_sel_hi:[0,1]
	ds_write_b16 v75, v23
	v_mul_f32_e32 v23, v27, v29
	v_cvt_pk_bf16_f32 v23, v23, s0
	ds_write_b16 v75, v23 offset:17408
	v_add_f32_e32 v23, v188, v192
	v_pk_mul_f32 v[184:185], v[184:185], v[28:29]
	v_exp_f32_e32 v28, v23
	v_perm_b32 v27, v165, v165, v32
	v_exp_f32_e64 v26, -v23
	v_mul_f32_e32 v23, v28, v27
	v_cvt_pk_bf16_f32 v23, v23, s0
	ds_write_b16 v76, v23
	v_add_f32_e32 v23, v189, v192
	v_exp_f32_e32 v28, v23
	v_perm_b32 v187, v168, v168, v32
	v_exp_f32_e64 v27, -v23
	v_mul_f32_e32 v23, v28, v187
	v_perm_b32 v28, v166, v166, v32
	global_load_dword v164, v200, s[80:81]
	global_load_dword v165, v201, s[80:81]
	global_load_dword v166, v202, s[80:81]
	s_add_u32 s80, s80, s98
	s_addc_u32 s81, s81, s99
	v_mul_f32_e32 v186, v26, v28
	v_cvt_pk_bf16_f32 v23, v23, s0
	v_perm_b32 v29, v169, v169, v1
	global_load_dword v167, v200, s[80:81]
	global_load_dword v168, v201, s[80:81]
	global_load_dword v169, v202, s[80:81]
	s_add_u32 s80, s80, s98
	s_addc_u32 s81, s81, s99
	v_cvt_pk_bf16_f32 v186, v186, s0
	ds_write_b16 v76, v186 offset:17408
	v_pk_mul_f32 v[186:187], v[22:23], v[26:27] op_sel_hi:[0,1]
	ds_write_b16 v77, v23
	v_mul_f32_e32 v23, v27, v29
	v_cvt_pk_bf16_f32 v23, v23, s0
	ds_write_b16 v77, v23 offset:17408
	v_add_f32_e32 v23, v190, v192
	v_exp_f32_e32 v27, v23
	v_perm_b32 v26, v171, v171, v32
	v_pk_mul_f32 v[186:187], v[186:187], v[28:29]
	v_exp_f32_e64 v28, -v23
	v_mul_f32_e32 v23, v27, v26
	v_cvt_pk_bf16_f32 v23, v23, s0
	ds_write_b16 v78, v23
	v_add_f32_e32 v23, v191, v192
	v_exp_f32_e32 v26, v23
	s_waitcnt vmcnt(43)
	v_exp_f32_e64 v29, -v23
	v_perm_b32 v27, v174, v174, v32
	v_perm_b32 v189, v175, v175, v1
	v_perm_b32 v188, v172, v172, v32
	global_load_dword v170, v200, s[80:81]
	global_load_dword v171, v201, s[80:81]
	global_load_dword v172, v202, s[80:81]
	s_add_u32 s80, s80, s98
	s_addc_u32 s81, s81, s99
	global_load_dword v173, v200, s[80:81]
	global_load_dword v174, v201, s[80:81]
	global_load_dword v175, v202, s[80:81]
	v_mul_f32_e32 v23, v26, v27
	v_mul_f32_e32 v26, v28, v188
	v_cvt_pk_bf16_f32 v23, v23, s0
	v_cvt_pk_bf16_f32 v26, v26, s0
	ds_write_b16 v78, v26 offset:17408
	ds_write_b16 v79, v23
	v_mul_f32_e32 v23, v29, v189
	v_cvt_pk_bf16_f32 v23, v23, s0
	v_pk_mul_f32 v[28:29], v[22:23], v[28:29] op_sel_hi:[0,1]
	v_cvt_pk_bf16_f32 v24, v24, v25
	v_cvt_pk_bf16_f32 v25, v176, v177
	v_cvt_pk_bf16_f32 v26, v178, v179
	v_cvt_pk_bf16_f32 v27, v180, v181
	v_pk_mul_f32 v[28:29], v[28:29], v[188:189]
	ds_write_b16 v79, v23 offset:17408
	v_cvt_pk_bf16_f32 v176, v182, v183
	v_cvt_pk_bf16_f32 v177, v184, v185
	v_cvt_pk_bf16_f32 v178, v186, v187
	v_cvt_pk_bf16_f32 v179, v28, v29
	ds_write_b128 v57, v[24:27] offset:34816
	ds_write_b128 v57, v[176:179] offset:34832
	s_and_saveexec_b64 s[72:73], s[0:1]
	ds_write_b32 v61, v22
	s_or_b64 exec, exec, s[72:73]
	s_cmp_eq_u32 s75, -1
	s_mov_b32 s10, s76
	s_waitcnt vmcnt(48)
	ds_write_b16 v58, v18 offset:53248
	ds_write_b16_d16_hi v58, v18 offset:53392
	ds_write_b16 v58, v19 offset:53536
	ds_write_b16_d16_hi v58, v19 offset:53680
	ds_write_b16 v58, v20 offset:53824
	ds_write_b16_d16_hi v58, v20 offset:53968
	ds_write_b16 v58, v21 offset:54112
	ds_write_b16_d16_hi v59, v21 offset:53248
	s_cbranch_scc1 .LBB0_1325
	s_cmp_gt_u32 s57, 2
	s_mov_b64 s[72:73], -1
	s_cbranch_scc0 .LBB0_1322
	s_and_b64 s[10:11], s[70:71], exec
	s_cselect_b32 s10, s74, s75
	s_add_i32 s10, s10, s65
	s_mov_b64 s[72:73], 0

.LBB0_1324:
	s_and_b64 s[72:73], s[70:71], exec
	s_cselect_b32 s72, 0xfffe2000, 0
	s_cselect_b32 s73, -1, 0
	s_add_u32 s80, s80, s72
	s_addc_u32 s81, s81, s73
	global_load_dwordx4 v[18:21], v203, s[80:81]
.LBB0_1325:
	s_cmp_gt_u32 s57, 3
	s_cselect_b64 s[72:73], -1, 0
	s_cmp_lt_u32 s57, 4
	s_waitcnt lgkmcnt(0)
	s_barrier
	s_cbranch_scc1 .LBB0_1331
	v_mov_b32_e32 v22, 0
	v_mov_b32_e32 v23, 0
	v_mov_b32_e32 v24, 0
	v_mov_b32_e32 v25, 0
	v_mov_b32_e32 v26, 0
	v_mov_b32_e32 v27, 0
	v_mov_b32_e32 v28, 0
	v_mov_b32_e32 v29, 0
	ds_read_b128 v[176:179], v81
	ds_read_b128 v[180:183], v80 offset:17408
	ds_read_b128 v[184:187], v83
	ds_read_b128 v[188:191], v82 offset:17408
	ds_read_b128 v[192:195], v84
	ds_read_b128 v[196:199], v80 offset:17536
	ds_read_b128 v[200:203], v86
	ds_read_b128 v[216:219], v85 offset:17408
	ds_read_b128 v[220:223], v87 offset:17408
	ds_read_b128 v[224:227], v88 offset:17408
	ds_read_b128 v[236:239], v89 offset:17408
	ds_read_b128 v[248:251], v90 offset:17408
	s_andn2_b64 vcc, exec, s[66:67]
	s_cbranch_vccnz .Lgl_p2a
	s_waitcnt lgkmcnt(10)
	v_mfma_f32_16x16x32_bf16 v[22:25], v[180:183], v[176:179], v[22:25]
	s_waitcnt lgkmcnt(8)
	v_mfma_f32_16x16x32_bf16 v[22:25], v[188:191], v[184:187], v[22:25]
	s_waitcnt lgkmcnt(6)
	v_mfma_f32_16x16x32_bf16 v[22:25], v[196:199], v[192:195], v[22:25]
	s_waitcnt lgkmcnt(4)
	v_mfma_f32_16x16x32_bf16 v[22:25], v[216:219], v[200:203], v[22:25]
.Lgl_p2a:
	s_andn2_b64 vcc, exec, s[68:69]
	s_cbranch_vccnz .Lgl_p2b
	s_waitcnt lgkmcnt(3)
	v_mfma_f32_16x16x32_bf16 v[26:29], v[220:223], v[176:179], v[26:29]
	s_waitcnt lgkmcnt(2)
	v_mfma_f32_16x16x32_bf16 v[26:29], v[224:227], v[184:187], v[26:29]
	s_waitcnt lgkmcnt(1)
	v_mfma_f32_16x16x32_bf16 v[26:29], v[236:239], v[192:195], v[26:29]
	s_waitcnt lgkmcnt(0)
	v_mfma_f32_16x16x32_bf16 v[26:29], v[248:251], v[200:203], v[26:29]
.Lgl_p2b:
	s_nop 7
	v_cndmask_b32_e64 v22, v22, 0, s[6:7]
	v_cndmask_b32_e64 v23, 0, v23, s[8:9]
	v_cvt_pk_bf16_f32 v22, v22, v23
	v_cndmask_b32_e64 v24, v24, 0, s[12:13]
	v_cndmask_b32_e64 v25, v25, 0, s[14:15]
	v_cvt_pk_bf16_f32 v23, v24, v25
	ds_write_b64 v102, v[22:23] offset:62464
	v_cndmask_b32_e64 v26, v26, 0, s[16:17]
	v_cndmask_b32_e64 v27, 0, v27, s[18:19]
	v_cvt_pk_bf16_f32 v26, v26, v27
	v_cndmask_b32_e64 v28, v28, 0, s[20:21]
	v_cndmask_b32_e64 v29, v29, 0, s[22:23]
	v_cvt_pk_bf16_f32 v27, v28, v29
	ds_write_b64 v102, v[26:27] offset:62496
.LBB0_1331:
	s_waitcnt lgkmcnt(0)
	s_barrier
	ds_read_b128 v[26:29], v60 offset:53248
	ds_read_b128 v[22:25], v60 offset:53312
	s_andn2_b64 vcc, exec, s[72:73]
	s_cbranch_vccnz .Lgl_su
	ds_read_b128 v[176:179], v104 offset:62464
	ds_read_b128 v[180:183], v104 offset:62528
	ds_read_b128 v[184:187], v62
	ds_read_b128 v[188:191], v92
	ds_read_b128 v[192:195], v62 offset:64
	ds_read_b128 v[196:199], v93
	ds_read_b128 v[200:203], v62 offset:128
	ds_read_b128 v[216:219], v94
	ds_read_b128 v[220:223], v62 offset:192
	ds_read_b128 v[224:227], v95
	s_waitcnt lgkmcnt(9)
	v_mfma_f32_16x16x32_bf16 v[248:251], v[26:29], v[176:179], 0
	ds_read_b128 v[176:179], v105 offset:62464
	s_waitcnt lgkmcnt(9)
	v_mfma_f32_16x16x32_bf16 v[248:251], v[22:25], v[180:183], v[248:251]
	ds_read_b128 v[180:183], v105 offset:62528
	s_waitcnt lgkmcnt(8)
	v_mfma_f32_16x16x32_bf16 v[248:251], v[184:187], v[188:191], v[248:251]
	ds_read_b128 v[188:191], v97
	s_waitcnt lgkmcnt(7)
	v_mfma_f32_16x16x32_bf16 v[248:251], v[192:195], v[196:199], v[248:251]
	ds_read_b128 v[196:199], v98
	s_waitcnt lgkmcnt(6)
	v_mfma_f32_16x16x32_bf16 v[248:251], v[200:203], v[216:219], v[248:251]
	ds_read_b128 v[216:219], v99
	s_waitcnt lgkmcnt(5)
	v_mfma_f32_16x16x32_bf16 v[248:251], v[220:223], v[224:227], v[248:251]
	ds_read_b128 v[224:227], v100
	s_waitcnt lgkmcnt(5)
	v_mfma_f32_16x16x32_bf16 v[236:239], v[26:29], v[176:179], 0
	ds_read_b128 v[176:179], v101
	s_waitcnt lgkmcnt(5)
	v_mfma_f32_16x16x32_bf16 v[236:239], v[22:25], v[180:183], v[236:239]
	ds_read_b128 v[180:183], v106 offset:34816
	s_waitcnt lgkmcnt(5)
	v_mfma_f32_16x16x32_bf16 v[236:239], v[184:187], v[188:191], v[236:239]
	ds_read_b128 v[184:187], v106 offset:34880
	ds_read_b128 v[188:191], v101 offset:64
	s_waitcnt lgkmcnt(6)
	v_mfma_f32_16x16x32_bf16 v[236:239], v[192:195], v[196:199], v[236:239]
	ds_read_b128 v[192:195], v107 offset:34816
	ds_read_b128 v[196:199], v107 offset:34880
	s_waitcnt lgkmcnt(7)
	v_mfma_f32_16x16x32_bf16 v[236:239], v[200:203], v[216:219], v[236:239]
	ds_read_b128 v[200:203], v101 offset:128
	ds_read_b128 v[216:219], v108 offset:34816
	s_waitcnt lgkmcnt(8)
	v_mfma_f32_16x16x32_bf16 v[236:239], v[220:223], v[224:227], v[236:239]
	ds_read_b128 v[220:223], v108 offset:34880
	ds_read_b128 v[224:227], v101 offset:192
	s_waitcnt lgkmcnt(9)
	v_pk_mul_f32 v[4:5], v[4:5], v[178:179]
	v_pk_mul_f32 v[2:3], v[2:3], v[176:177]
	ds_read_b128 v[176:179], v109 offset:34816
	s_nop 0
	s_waitcnt lgkmcnt(9)
	v_mfma_f32_16x16x32_bf16 v[2:5], v[180:183], v[26:29], v[2:5]
	ds_read_b128 v[180:183], v109 offset:34880
	s_waitcnt lgkmcnt(9)
	v_mfma_f32_16x16x32_bf16 v[2:5], v[184:187], v[22:25], v[2:5]
	s_waitcnt lgkmcnt(8)
	v_pk_mul_f32 v[16:17], v[16:17], v[190:191]
	v_pk_mul_f32 v[14:15], v[14:15], v[188:189]
	s_nop 1
	s_waitcnt lgkmcnt(7)
	v_mfma_f32_16x16x32_bf16 v[14:17], v[192:195], v[26:29], v[14:17]
	s_waitcnt lgkmcnt(6)
	v_mfma_f32_16x16x32_bf16 v[14:17], v[196:199], v[22:25], v[14:17]
	s_waitcnt lgkmcnt(5)
	v_pk_mul_f32 v[8:9], v[8:9], v[202:203]
	v_pk_mul_f32 v[6:7], v[6:7], v[200:201]
	s_nop 1
	s_waitcnt lgkmcnt(4)
	v_mfma_f32_16x16x32_bf16 v[6:9], v[216:219], v[26:29], v[6:9]
	s_waitcnt lgkmcnt(3)
	v_mfma_f32_16x16x32_bf16 v[6:9], v[220:223], v[22:25], v[6:9]
	s_waitcnt lgkmcnt(2)
	v_pk_mul_f32 v[12:13], v[12:13], v[226:227]
	v_pk_mul_f32 v[10:11], v[10:11], v[224:225]
	s_nop 1
	s_waitcnt lgkmcnt(1)
	v_mfma_f32_16x16x32_bf16 v[10:13], v[176:179], v[26:29], v[10:13]
	s_waitcnt lgkmcnt(0)
	v_mfma_f32_16x16x32_bf16 v[10:13], v[180:183], v[22:25], v[10:13]
	v_add_u32_e32 v204, s76, v41
	v_ashrrev_i32_e32 v205, 31, v204
	v_cvt_pk_bf16_f32 v248, v248, v249
	v_cvt_pk_bf16_f32 v249, v250, v251
	v_lshlrev_b64 v[250:251], 11, v[204:205]
	v_lshl_add_u64 v[250:251], v[50:51], 0, v[250:251]
	global_store_dwordx2 v[250:251], v[248:249], off nt
	v_add_u32_e32 v204, s76, v142
	v_ashrrev_i32_e32 v205, 31, v204
	v_cvt_pk_bf16_f32 v236, v236, v237
	v_cvt_pk_bf16_f32 v237, v238, v239
	v_lshlrev_b64 v[238:239], 11, v[204:205]
	v_lshl_add_u64 v[238:239], v[50:51], 0, v[238:239]
	global_store_dwordx2 v[238:239], v[236:237], off nt
	s_branch .LBB0_1316
.Lgl_su:
	ds_read_b128 v[176:179], v101
	ds_read_b128 v[180:183], v106 offset:34816
	ds_read_b128 v[184:187], v106 offset:34880
	ds_read_b128 v[188:191], v101 offset:64
	ds_read_b128 v[192:195], v107 offset:34816
	ds_read_b128 v[196:199], v107 offset:34880
	ds_read_b128 v[200:203], v101 offset:128
	ds_read_b128 v[216:219], v108 offset:34816
	ds_read_b128 v[220:223], v108 offset:34880
	ds_read_b128 v[224:227], v101 offset:192
	ds_read_b128 v[236:239], v109 offset:34816
	ds_read_b128 v[248:251], v109 offset:34880
	s_waitcnt lgkmcnt(11)
	v_pk_mul_f32 v[4:5], v[4:5], v[178:179]
	v_pk_mul_f32 v[2:3], v[2:3], v[176:177]
	s_nop 1
	s_waitcnt lgkmcnt(10)
	v_mfma_f32_16x16x32_bf16 v[2:5], v[180:183], v[26:29], v[2:5]
	s_waitcnt lgkmcnt(9)
	v_mfma_f32_16x16x32_bf16 v[2:5], v[184:187], v[22:25], v[2:5]
	s_waitcnt lgkmcnt(8)
	v_pk_mul_f32 v[16:17], v[16:17], v[190:191]
	v_pk_mul_f32 v[14:15], v[14:15], v[188:189]
	s_nop 1
	s_waitcnt lgkmcnt(7)
	v_mfma_f32_16x16x32_bf16 v[14:17], v[192:195], v[26:29], v[14:17]
	s_waitcnt lgkmcnt(6)
	v_mfma_f32_16x16x32_bf16 v[14:17], v[196:199], v[22:25], v[14:17]
	s_waitcnt lgkmcnt(5)
	v_pk_mul_f32 v[8:9], v[8:9], v[202:203]
	v_pk_mul_f32 v[6:7], v[6:7], v[200:201]
	s_nop 1
	s_waitcnt lgkmcnt(4)
	v_mfma_f32_16x16x32_bf16 v[6:9], v[216:219], v[26:29], v[6:9]
	s_waitcnt lgkmcnt(3)
	v_mfma_f32_16x16x32_bf16 v[6:9], v[220:223], v[22:25], v[6:9]
	s_waitcnt lgkmcnt(2)
	v_pk_mul_f32 v[12:13], v[12:13], v[226:227]
	v_pk_mul_f32 v[10:11], v[10:11], v[224:225]
	s_nop 1
	s_waitcnt lgkmcnt(1)
	v_mfma_f32_16x16x32_bf16 v[10:13], v[236:239], v[26:29], v[10:13]
	s_waitcnt lgkmcnt(0)
	v_mfma_f32_16x16x32_bf16 v[10:13], v[248:251], v[22:25], v[10:13]
	s_branch .LBB0_1316
